# instruction selection in the attention softmax segment: NaN-canonicalising self-max instructions removed from the serial row-max chain (5 VALU per tile off the chain)
# speedup vs baseline: 1.0042x; 1.0042x over previous
; __device__ __forceinline__ void partialSM(f32x16& p0, f32x16& p1, float& m_reg, float& mn, float& alpha) {
;   float pmax = p0[0];
; #pragma unroll
;   for (int r = 1; r < 16; ++r) pmax = fmaxf(pmax, p0[r]);
; #pragma unroll
;   for (int r = 0; r < 16; ++r) pmax = fmaxf(pmax, p1[r]);
;   { auto rr = __builtin_amdgcn_permlane32_swap(__float_as_uint(pmax), __float_as_uint(pmax), false, false);
;     pmax = fmaxf(__uint_as_float(rr[0]), __uint_as_float(rr[1])); }
;   if (__builtin_expect(__all(pmax - m_reg <= THRL), 1)) { mn = m_reg; alpha = 1.f; }
;   else { mn = fmaxf(m_reg, pmax); alpha = __builtin_amdgcn_exp2f(m_reg - mn); m_reg = mn; }
.LBB0_1103:
	v_max_f32_e32 v33, v96, v97
	v_max3_f32 v33, v33, v98, v99
	v_max3_f32 v33, v33, v100, v101
	v_max3_f32 v33, v33, v102, v103
	v_max3_f32 v33, v33, v104, v105
	v_max3_f32 v33, v33, v106, v107
	v_max3_f32 v33, v33, v108, v109
	v_max3_f32 v33, v33, v110, v111
	v_max3_f32 v33, v33, v80, v81
	v_max3_f32 v33, v33, v82, v83
	v_max3_f32 v33, v33, v84, v85
	v_max3_f32 v33, v33, v86, v87
	v_max3_f32 v33, v33, v88, v89
	v_max3_f32 v33, v33, v90, v91
	v_max3_f32 v33, v33, v92, v93
	v_max3_f32 v33, v33, v94, v95
	v_mov_b32_e32 v34, v33
	s_nop 1
	v_permlane32_swap_b32_e32 v33, v34
	v_max_f32_e32 v33, v33, v34
	v_sub_f32_e32 v34, v33, v160
	v_max_f32_e32 v33, v160, v33
	v_sub_f32_e32 v35, v160, v33
	v_exp_f32_e32 v35, v35
	v_cmp_ge_f32_e32 vcc, s69, v34
	s_cmp_eq_u64 vcc, exec
	s_cselect_b64 s[4:5], -1, 0
	v_cndmask_b32_e64 v46, v35, 1.0, s[4:5]
	v_cmp_gt_f32_e32 vcc, 1.0, v46
	s_cbranch_vccz .LBB0_1107
	s_and_saveexec_b64 s[30:31], s[0:1]
	ds_write_b32 v208, v46 offset:128
	s_or_b64 exec, exec, s[30:31]
	s_waitcnt lgkmcnt(0)
	ds_read_b128 v[34:37], v185 offset:224
	ds_read_b128 v[38:41], v185 offset:192
	ds_read_b128 v[42:45], v185 offset:160
	ds_read_b128 v[214:217], v185 offset:128
	s_waitcnt lgkmcnt(0)
	v_pk_mul_f32 v[76:77], v[76:77], v[34:35]
	v_pk_mul_f32 v[72:73], v[72:73], v[38:39]
	v_pk_mul_f32 v[68:69], v[68:69], v[42:43]
	v_pk_mul_f32 v[78:79], v[78:79], v[36:37]
	v_pk_mul_f32 v[74:75], v[74:75], v[40:41]
	v_pk_mul_f32 v[70:71], v[70:71], v[44:45]
	v_pk_mul_f32 v[66:67], v[66:67], v[216:217]
	v_pk_mul_f32 v[64:65], v[64:65], v[214:215]
	v_pk_mul_f32 v[60:61], v[60:61], v[34:35]
	v_pk_mul_f32 v[56:57], v[56:57], v[38:39]
	v_pk_mul_f32 v[52:53], v[52:53], v[42:43]
	v_pk_mul_f32 v[62:63], v[62:63], v[36:37]
	v_pk_mul_f32 v[58:59], v[58:59], v[40:41]
	v_pk_mul_f32 v[54:55], v[54:55], v[44:45]
	v_pk_mul_f32 v[50:51], v[50:51], v[216:217]
	v_pk_mul_f32 v[48:49], v[48:49], v[214:215]
	v_pk_mul_f32 v[28:29], v[28:29], v[34:35]
	v_pk_mul_f32 v[24:25], v[24:25], v[38:39]
	v_pk_mul_f32 v[20:21], v[20:21], v[42:43]
	v_pk_mul_f32 v[30:31], v[30:31], v[36:37]
	v_pk_mul_f32 v[26:27], v[26:27], v[40:41]
	v_pk_mul_f32 v[22:23], v[22:23], v[44:45]
	v_pk_mul_f32 v[18:19], v[18:19], v[216:217]
	v_pk_mul_f32 v[16:17], v[16:17], v[214:215]
	v_pk_mul_f32 v[12:13], v[12:13], v[34:35]
	v_pk_mul_f32 v[8:9], v[8:9], v[38:39]
	v_pk_mul_f32 v[4:5], v[4:5], v[42:43]
	v_pk_mul_f32 v[14:15], v[14:15], v[36:37]
	v_pk_mul_f32 v[10:11], v[10:11], v[40:41]
	v_pk_mul_f32 v[6:7], v[6:7], v[44:45]
	v_pk_mul_f32 v[2:3], v[2:3], v[216:217]
	v_pk_mul_f32 v[0:1], v[0:1], v[214:215]

; __device__ __forceinline__ void partialSM(f32x16& p0, f32x16& p1, float& m_reg, float& mn, float& alpha) {
;   float pmax = p0[0];
; #pragma unroll
;   for (int r = 1; r < 16; ++r) pmax = fmaxf(pmax, p0[r]);
; #pragma unroll
;   for (int r = 0; r < 16; ++r) pmax = fmaxf(pmax, p1[r]);
;   { auto rr = __builtin_amdgcn_permlane32_swap(__float_as_uint(pmax), __float_as_uint(pmax), false, false);
;     pmax = fmaxf(__uint_as_float(rr[0]), __uint_as_float(rr[1])); }
;   if (__builtin_expect(__all(pmax - m_reg <= THRL), 1)) { mn = m_reg; alpha = 1.f; }
;   else { mn = fmaxf(m_reg, pmax); alpha = __builtin_amdgcn_exp2f(m_reg - mn); m_reg = mn; }
.LBB0_1122:
	v_max_f32_e32 v34, v96, v97
	v_max3_f32 v34, v34, v98, v99
	v_max3_f32 v34, v34, v100, v101
	v_max3_f32 v34, v34, v102, v103
	v_max3_f32 v34, v34, v104, v105
	v_max3_f32 v34, v34, v106, v107
	v_max3_f32 v34, v34, v108, v109
	v_max3_f32 v34, v34, v110, v111
	v_max3_f32 v34, v34, v80, v81
	v_max3_f32 v34, v34, v82, v83
	v_max3_f32 v34, v34, v84, v85
	v_max3_f32 v34, v34, v86, v87
	v_max3_f32 v34, v34, v88, v89
	v_max3_f32 v34, v34, v90, v91
	v_max3_f32 v34, v34, v92, v93
	v_max3_f32 v34, v34, v94, v95
	v_mov_b32_e32 v35, v34
	s_nop 1
	v_permlane32_swap_b32_e32 v34, v35
	v_max_f32_e32 v34, v34, v35
	v_sub_f32_e32 v35, v34, v33
	v_max_f32_e32 v34, v33, v34
	v_sub_f32_e32 v36, v33, v34
	v_exp_f32_e32 v36, v36
	v_cmp_ge_f32_e32 vcc, s69, v35
	s_cmp_eq_u64 vcc, exec
	s_cselect_b64 s[6:7], -1, 0
	v_cndmask_b32_e64 v187, v36, 1.0, s[6:7]
	v_cmp_gt_f32_e32 vcc, 1.0, v187
	s_cbranch_vccz .LBB0_1126
	s_and_saveexec_b64 s[34:35], s[0:1]
	ds_write_b32 v208, v187 offset:128
	s_or_b64 exec, exec, s[34:35]
	s_waitcnt lgkmcnt(0)
	ds_read_b128 v[36:39], v185 offset:224
	ds_read_b128 v[40:43], v185 offset:192
	ds_read_b128 v[160:163], v185 offset:160
	ds_read_b128 v[214:217], v185 offset:128
	s_waitcnt lgkmcnt(0)
	v_pk_mul_f32 v[76:77], v[76:77], v[36:37]
	v_pk_mul_f32 v[72:73], v[72:73], v[40:41]
	v_pk_mul_f32 v[68:69], v[68:69], v[160:161]
	v_pk_mul_f32 v[78:79], v[78:79], v[38:39]
	v_pk_mul_f32 v[74:75], v[74:75], v[42:43]
	v_pk_mul_f32 v[70:71], v[70:71], v[162:163]
	v_pk_mul_f32 v[66:67], v[66:67], v[216:217]
	v_pk_mul_f32 v[64:65], v[64:65], v[214:215]
	v_pk_mul_f32 v[60:61], v[60:61], v[36:37]
	v_pk_mul_f32 v[56:57], v[56:57], v[40:41]
	v_pk_mul_f32 v[52:53], v[52:53], v[160:161]
	v_pk_mul_f32 v[62:63], v[62:63], v[38:39]
	v_pk_mul_f32 v[58:59], v[58:59], v[42:43]
	v_pk_mul_f32 v[54:55], v[54:55], v[162:163]
	v_pk_mul_f32 v[50:51], v[50:51], v[216:217]
	v_pk_mul_f32 v[48:49], v[48:49], v[214:215]
	v_pk_mul_f32 v[28:29], v[28:29], v[36:37]
	v_pk_mul_f32 v[24:25], v[24:25], v[40:41]
	v_pk_mul_f32 v[20:21], v[20:21], v[160:161]
	v_pk_mul_f32 v[30:31], v[30:31], v[38:39]
	v_pk_mul_f32 v[26:27], v[26:27], v[42:43]
	v_pk_mul_f32 v[22:23], v[22:23], v[162:163]
	v_pk_mul_f32 v[18:19], v[18:19], v[216:217]
	v_pk_mul_f32 v[16:17], v[16:17], v[214:215]
	v_pk_mul_f32 v[12:13], v[12:13], v[36:37]
	v_pk_mul_f32 v[8:9], v[8:9], v[40:41]
	v_pk_mul_f32 v[4:5], v[4:5], v[160:161]
	v_pk_mul_f32 v[14:15], v[14:15], v[38:39]
	v_pk_mul_f32 v[10:11], v[10:11], v[42:43]
	v_pk_mul_f32 v[6:7], v[6:7], v[162:163]
	v_pk_mul_f32 v[2:3], v[2:3], v[216:217]
	v_pk_mul_f32 v[0:1], v[0:1], v[214:215]

; __device__ __forceinline__ void partialSM(f32x16& p0, f32x16& p1, float& m_reg, float& mn, float& alpha) {
;   float pmax = p0[0];
; #pragma unroll
;   for (int r = 1; r < 16; ++r) pmax = fmaxf(pmax, p0[r]);
; #pragma unroll
;   for (int r = 0; r < 16; ++r) pmax = fmaxf(pmax, p1[r]);
;   { auto rr = __builtin_amdgcn_permlane32_swap(__float_as_uint(pmax), __float_as_uint(pmax), false, false);
;     pmax = fmaxf(__uint_as_float(rr[0]), __uint_as_float(rr[1])); }
;   if (__builtin_expect(__all(pmax - m_reg <= THRL), 1)) { mn = m_reg; alpha = 1.f; }
;   else { mn = fmaxf(m_reg, pmax); alpha = __builtin_amdgcn_exp2f(m_reg - mn); m_reg = mn; }
.LBB0_1147:
	v_max_f32_e32 v34, v96, v97
	v_max3_f32 v34, v34, v98, v99
	v_max3_f32 v34, v34, v100, v101
	v_max3_f32 v34, v34, v102, v103
	v_max3_f32 v34, v34, v104, v105
	v_max3_f32 v34, v34, v106, v107
	v_max3_f32 v34, v34, v108, v109
	v_max3_f32 v34, v34, v110, v111
	v_max3_f32 v34, v34, v80, v81
	v_max3_f32 v34, v34, v82, v83
	v_max3_f32 v34, v34, v84, v85
	v_max3_f32 v34, v34, v86, v87
	v_max3_f32 v34, v34, v88, v89
	v_max3_f32 v34, v34, v90, v91
	v_max3_f32 v34, v34, v92, v93
	v_max3_f32 v34, v34, v94, v95
	v_mov_b32_e32 v35, v34
	s_nop 1
	v_permlane32_swap_b32_e32 v34, v35
	v_max_f32_e32 v34, v34, v35
	v_max_f32_e32 v35, v33, v33
	v_max_f32_e32 v35, v35, v34
	v_sub_f32_e32 v36, v34, v33
	v_sub_f32_e32 v34, v33, v35
	v_exp_f32_e32 v34, v34
	v_cmp_ge_f32_e32 vcc, s69, v36
	s_cmp_eq_u64 vcc, exec
	s_cselect_b64 s[6:7], -1, 0
	v_cndmask_b32_e64 v34, v34, 1.0, s[6:7]
	v_cmp_gt_f32_e32 vcc, 1.0, v34
	s_cbranch_vccz .LBB0_1151
	s_and_saveexec_b64 s[34:35], s[0:1]
	ds_write_b32 v208, v34 offset:128
	s_or_b64 exec, exec, s[34:35]
	s_waitcnt lgkmcnt(0)
	ds_read_b128 v[36:39], v185 offset:224
	ds_read_b128 v[40:43], v185 offset:192
	ds_read_b128 v[160:163], v185 offset:160
	ds_read_b128 v[214:217], v185 offset:128
	s_waitcnt lgkmcnt(0)
	v_pk_mul_f32 v[76:77], v[76:77], v[36:37]
	v_pk_mul_f32 v[72:73], v[72:73], v[40:41]
	v_pk_mul_f32 v[68:69], v[68:69], v[160:161]
	v_pk_mul_f32 v[78:79], v[78:79], v[38:39]
	v_pk_mul_f32 v[74:75], v[74:75], v[42:43]
	v_pk_mul_f32 v[70:71], v[70:71], v[162:163]
	v_pk_mul_f32 v[66:67], v[66:67], v[216:217]
	v_pk_mul_f32 v[64:65], v[64:65], v[214:215]
	v_pk_mul_f32 v[60:61], v[60:61], v[36:37]
	v_pk_mul_f32 v[56:57], v[56:57], v[40:41]
	v_pk_mul_f32 v[52:53], v[52:53], v[160:161]
	v_pk_mul_f32 v[62:63], v[62:63], v[38:39]
	v_pk_mul_f32 v[58:59], v[58:59], v[42:43]
	v_pk_mul_f32 v[54:55], v[54:55], v[162:163]
	v_pk_mul_f32 v[50:51], v[50:51], v[216:217]
	v_pk_mul_f32 v[48:49], v[48:49], v[214:215]
	v_pk_mul_f32 v[28:29], v[28:29], v[36:37]
	v_pk_mul_f32 v[24:25], v[24:25], v[40:41]
	v_pk_mul_f32 v[20:21], v[20:21], v[160:161]
	v_pk_mul_f32 v[30:31], v[30:31], v[38:39]
	v_pk_mul_f32 v[26:27], v[26:27], v[42:43]
	v_pk_mul_f32 v[22:23], v[22:23], v[162:163]
	v_pk_mul_f32 v[18:19], v[18:19], v[216:217]
	v_pk_mul_f32 v[16:17], v[16:17], v[214:215]
	v_pk_mul_f32 v[12:13], v[12:13], v[36:37]
	v_pk_mul_f32 v[8:9], v[8:9], v[40:41]
	v_pk_mul_f32 v[4:5], v[4:5], v[160:161]
	v_pk_mul_f32 v[14:15], v[14:15], v[38:39]
	v_pk_mul_f32 v[10:11], v[10:11], v[42:43]
	v_pk_mul_f32 v[6:7], v[6:7], v[162:163]
	v_pk_mul_f32 v[2:3], v[2:3], v[216:217]
	v_pk_mul_f32 v[0:1], v[0:1], v[214:215]
